# grid barrier: the mid arriver of each XCD issues an early L2 writeback (non-blocking) so the last arriver's flush is shorter
# speedup vs baseline: 1.0017x; 1.0017x over previous
.LBB0_1043:
	s_or_b64 exec, exec, s[2:3]
	s_waitcnt vmcnt(0)
	v_readfirstlane_b32 s2, v1
	v_readlane_b32 s3, v255, 10
	v_readlane_b32 s98, v255, 6
	s_add_i32 s99, s3, -1
	s_mul_i32 s99, s99, s98
	s_lshr_b32 s98, s98, 1
	s_add_i32 s99, s99, s98
	s_cmp_lg_u32 s2, s99
	s_cbranch_scc1 .Lbar_noflush
	buffer_wbl2 sc1
.Lbar_noflush:
	s_nop 0
	v_add3_u32 v0, s2, v0, 1
	v_readlane_b32 s2, v255, 6
	s_mul_i32 s2, s3, s2
	s_nop 0
	v_cmp_ne_u32_e32 vcc, s2, v0
	s_and_saveexec_b64 s[2:3], vcc
	s_xor_b64 s[2:3], exec, s[2:3]
	s_cbranch_execz .LBB0_1047
	v_readlane_b32 s4, v254, 23
	v_readlane_b32 s5, v254, 24
	v_readlane_b32 s6, v255, 10
	s_nop 3
	global_load_dword v0, v193, s[4:5] sc1
	s_waitcnt vmcnt(0)
	v_cmp_le_u32_e32 vcc, s6, v0
	s_cbranch_vccnz .LBB0_1046
